# M-split half tiles (FF2, G_out): A-fragment LDS reads for the absent row half skipped under a wave-uniform branch
# baseline (speedup 1.0000x reference)
.LBB0_68:
	s_add_u32 s21, s54, s56
	s_addc_u32 s36, s55, s57
	s_add_u32 s21, s21, 0x100
	s_addc_u32 s64, s36, 0
	s_add_u32 s94, s96, s56
	s_addc_u32 s65, s97, s57
	s_add_i32 s95, 0, 0x10000
	s_cmpk_eq_i32 s56, 0x700
	s_cselect_b64 s[68:69], -1, 0
	s_and_b64 s[36:37], s[68:69], exec
	s_cselect_b32 s67, s43, s64
	s_cselect_b32 s66, s90, s21
	v_add_u32_e32 v80, s95, v239
	s_cselect_b32 s65, s41, s65
	s_cselect_b32 s64, s72, s94
	s_add_i32 s21, 0, 0x14000
	ds_read_b128 v[154:157], v80
	ds_read_b128 v[158:161], v80 offset:1024
	ds_read_b128 v[162:165], v80 offset:2048
	ds_read_b128 v[166:169], v80 offset:3072
	v_add_u32_e32 v80, s21, v239
	ds_read_b128 v[130:133], v80
	ds_read_b128 v[142:145], v80 offset:1024
	ds_read_b128 v[146:149], v80 offset:2048
	ds_read_b128 v[150:153], v80 offset:3072
	s_waitcnt lgkmcnt(0)
	v_lshl_add_u64 v[114:115], v[218:219], 0, s[56:57]
	s_add_i32 m0, s51, 0xc000
	ds_read_b128 v[170:173], v241
	ds_read_b128 v[174:177], v241 offset:1024
	ds_read_b128 v[178:181], v241 offset:2048
	ds_read_b128 v[182:185], v241 offset:3072
	ds_read_b128 v[186:189], v241 offset:4096
	ds_read_b128 v[190:193], v241 offset:5120
	ds_read_b128 v[198:201], v241 offset:6144
	ds_read_b128 v[220:223], v241 offset:7168
	global_load_lds_dwordx4 v[114:115], off
	v_lshl_add_u64 v[114:115], v[216:217], 0, s[56:57]
	s_add_i32 m0, s51, 0xe000
	s_nop 0
	global_load_lds_dwordx4 v[114:115], off
	s_waitcnt vmcnt(8)
	s_waitcnt lgkmcnt(0)
	s_barrier
	s_setprio 1
	s_waitcnt lgkmcnt(0)
	v_mfma_f32_16x16x32_bf16 v[114:117], v[154:157], v[170:173], v[138:141]
	v_mfma_f32_16x16x32_bf16 v[126:129], v[162:165], v[170:173], v[134:137]
	v_mfma_f32_16x16x32_bf16 v[122:125], v[154:157], v[178:181], v[122:125]
	v_mfma_f32_16x16x32_bf16 v[118:121], v[162:165], v[178:181], v[118:121]
	v_mfma_f32_16x16x32_bf16 v[110:113], v[154:157], v[186:189], v[110:113]
	v_mfma_f32_16x16x32_bf16 v[106:109], v[162:165], v[186:189], v[106:109]
	v_mfma_f32_16x16x32_bf16 v[102:105], v[154:157], v[198:201], v[102:105]
	v_mfma_f32_16x16x32_bf16 v[98:101], v[162:165], v[198:201], v[98:101]
	v_mfma_f32_16x16x32_bf16 v[114:117], v[158:161], v[174:177], v[114:117]
	v_mfma_f32_16x16x32_bf16 v[126:129], v[166:169], v[174:177], v[126:129]
	v_mfma_f32_16x16x32_bf16 v[122:125], v[158:161], v[182:185], v[122:125]
	v_mfma_f32_16x16x32_bf16 v[118:121], v[166:169], v[182:185], v[118:121]
	v_mfma_f32_16x16x32_bf16 v[110:113], v[158:161], v[190:193], v[110:113]
	v_mfma_f32_16x16x32_bf16 v[106:109], v[166:169], v[190:193], v[106:109]
	v_mfma_f32_16x16x32_bf16 v[102:105], v[158:161], v[220:223], v[102:105]
	v_mfma_f32_16x16x32_bf16 v[98:101], v[166:169], v[220:223], v[98:101]
	s_setprio 0
	s_setprio 1
	v_mfma_f32_16x16x32_bf16 v[86:89], v[130:133], v[170:173], v[86:89]
	v_mfma_f32_16x16x32_bf16 v[82:85], v[146:149], v[170:173], v[82:85]
	v_mfma_f32_16x16x32_bf16 v[68:71], v[130:133], v[178:181], v[68:71]
	v_mfma_f32_16x16x32_bf16 v[64:67], v[146:149], v[178:181], v[64:67]
	v_mfma_f32_16x16x32_bf16 v[52:55], v[130:133], v[186:189], v[52:55]
	v_mfma_f32_16x16x32_bf16 v[48:51], v[146:149], v[186:189], v[48:51]
	v_mfma_f32_16x16x32_bf16 v[36:39], v[130:133], v[198:201], v[36:39]
	v_mfma_f32_16x16x32_bf16 v[32:35], v[146:149], v[198:201], v[32:35]
	v_mfma_f32_16x16x32_bf16 v[86:89], v[142:145], v[174:177], v[86:89]
	v_mfma_f32_16x16x32_bf16 v[82:85], v[150:153], v[174:177], v[82:85]
	v_mfma_f32_16x16x32_bf16 v[68:71], v[142:145], v[182:185], v[68:71]
	v_mfma_f32_16x16x32_bf16 v[64:67], v[150:153], v[182:185], v[64:67]
	v_mfma_f32_16x16x32_bf16 v[52:55], v[142:145], v[190:193], v[52:55]
	v_mfma_f32_16x16x32_bf16 v[48:51], v[150:153], v[190:193], v[48:51]
	v_mfma_f32_16x16x32_bf16 v[36:39], v[142:145], v[220:223], v[36:39]
	v_mfma_f32_16x16x32_bf16 v[32:35], v[150:153], v[220:223], v[32:35]
	s_setprio 0
	s_barrier
	s_add_i32 s36, s95, s79
	v_lshl_add_u64 v[220:221], s[64:65], 0, v[206:207]
	s_mov_b32 m0, s36
	s_cmp_lg_u64 s[62:63], 0
	s_cbranch_scc0 .Lhm_go1
	ds_read_b128 v[186:189], v241 offset:16384
	ds_read_b128 v[190:193], v241 offset:17408
	ds_read_b128 v[178:181], v241 offset:18432
	ds_read_b128 v[182:185], v241 offset:19456
	ds_read_b128 v[170:173], v241 offset:20480
	ds_read_b128 v[174:177], v241 offset:21504
	ds_read_b128 v[134:137], v241 offset:22528
	ds_read_b128 v[138:141], v241 offset:23552
.Lhm_go1:
	global_load_lds_dwordx4 v[220:221], off
	s_add_i32 m0, s36, 0x2000
	s_add_u32 s36, s64, 0x40000
	v_lshl_add_u64 v[222:223], s[64:65], 0, v[210:211]
	s_addc_u32 s37, s65, 0
	s_add_i32 s21, s21, s79
	global_load_lds_dwordx4 v[222:223], off
	v_lshl_add_u64 v[198:199], s[36:37], 0, v[206:207]
	s_mov_b32 m0, s21
	v_lshl_add_u64 v[224:225], s[66:67], 0, v[194:195]
	global_load_lds_dwordx4 v[198:199], off
	v_lshl_add_u64 v[198:199], s[36:37], 0, v[210:211]
	s_add_i32 m0, s21, 0x2000
	v_lshl_add_u64 v[226:227], s[66:67], 0, v[208:209]
	global_load_lds_dwordx4 v[198:199], off
	s_mov_b32 m0, s51
	v_cndmask_b32_e64 v80, 0, 1, s[62:63]
	global_load_lds_dwordx4 v[224:225], off
	s_mov_b32 m0, s53
	v_cmp_ne_u32_e64 s[36:37], 1, v80
	global_load_lds_dwordx4 v[226:227], off
	s_waitcnt vmcnt(8)
	s_waitcnt lgkmcnt(0)
	s_andn2_b64 vcc, exec, s[62:63]
	s_barrier
	s_cbranch_vccnz .LBB0_70
	s_setprio 1
	s_waitcnt lgkmcnt(0)
	v_mfma_f32_16x16x32_bf16 v[94:97], v[154:157], v[186:189], v[94:97]
	v_mfma_f32_16x16x32_bf16 v[90:93], v[162:165], v[186:189], v[90:93]
	v_mfma_f32_16x16x32_bf16 v[76:79], v[154:157], v[178:181], v[76:79]
	v_mfma_f32_16x16x32_bf16 v[72:75], v[162:165], v[178:181], v[72:75]
	v_mfma_f32_16x16x32_bf16 v[60:63], v[154:157], v[170:173], v[60:63]
	v_mfma_f32_16x16x32_bf16 v[56:59], v[162:165], v[170:173], v[56:59]
	v_mfma_f32_16x16x32_bf16 v[44:47], v[154:157], v[134:137], v[44:47]
	v_mfma_f32_16x16x32_bf16 v[40:43], v[162:165], v[134:137], v[40:43]
	v_mfma_f32_16x16x32_bf16 v[94:97], v[158:161], v[190:193], v[94:97]
	v_mfma_f32_16x16x32_bf16 v[90:93], v[166:169], v[190:193], v[90:93]
	v_mfma_f32_16x16x32_bf16 v[76:79], v[158:161], v[182:185], v[76:79]
	v_mfma_f32_16x16x32_bf16 v[72:75], v[166:169], v[182:185], v[72:75]
	v_mfma_f32_16x16x32_bf16 v[60:63], v[158:161], v[174:177], v[60:63]
	v_mfma_f32_16x16x32_bf16 v[56:59], v[166:169], v[174:177], v[56:59]
	v_mfma_f32_16x16x32_bf16 v[44:47], v[158:161], v[138:141], v[44:47]
	v_mfma_f32_16x16x32_bf16 v[40:43], v[166:169], v[138:141], v[40:43]
	s_setprio 0
	s_setprio 1
	v_mfma_f32_16x16x32_bf16 v[28:31], v[130:133], v[186:189], v[28:31]
	v_mfma_f32_16x16x32_bf16 v[24:27], v[146:149], v[186:189], v[24:27]
	v_mfma_f32_16x16x32_bf16 v[20:23], v[130:133], v[178:181], v[20:23]
	v_mfma_f32_16x16x32_bf16 v[16:19], v[146:149], v[178:181], v[16:19]
	v_mfma_f32_16x16x32_bf16 v[12:15], v[130:133], v[170:173], v[12:15]
	v_mfma_f32_16x16x32_bf16 v[8:11], v[146:149], v[170:173], v[8:11]
	v_mfma_f32_16x16x32_bf16 v[4:7], v[130:133], v[134:137], v[4:7]
	v_mfma_f32_16x16x32_bf16 v[0:3], v[146:149], v[134:137], v[0:3]
	v_mfma_f32_16x16x32_bf16 v[28:31], v[142:145], v[190:193], v[28:31]
	v_mfma_f32_16x16x32_bf16 v[24:27], v[150:153], v[190:193], v[24:27]
	v_mfma_f32_16x16x32_bf16 v[20:23], v[142:145], v[182:185], v[20:23]
	v_mfma_f32_16x16x32_bf16 v[16:19], v[150:153], v[182:185], v[16:19]
	v_mfma_f32_16x16x32_bf16 v[12:15], v[142:145], v[174:177], v[12:15]
	v_mfma_f32_16x16x32_bf16 v[8:11], v[150:153], v[174:177], v[8:11]
	v_mfma_f32_16x16x32_bf16 v[4:7], v[142:145], v[138:141], v[4:7]
	v_mfma_f32_16x16x32_bf16 v[0:3], v[150:153], v[138:141], v[0:3]
	s_setprio 0
.LBB0_70:
	s_barrier
	s_add_i32 s21, 0, 0x18000
	v_add_u32_e32 v80, s21, v239
	s_add_i32 s94, 0, 0x1c000
	ds_read_b128 v[154:157], v80
	ds_read_b128 v[158:161], v80 offset:1024
	ds_read_b128 v[162:165], v80 offset:2048
	ds_read_b128 v[166:169], v80 offset:3072
	v_add_u32_e32 v80, s94, v239
	ds_read_b128 v[130:133], v80
	ds_read_b128 v[142:145], v80 offset:1024
	ds_read_b128 v[146:149], v80 offset:2048
	ds_read_b128 v[150:153], v80 offset:3072
	s_and_b64 s[68:69], s[46:47], s[68:69]
	s_and_b64 s[68:69], s[68:69], exec
	s_cselect_b32 s69, s91, s10
	s_cselect_b32 s68, 0, 0
	s_add_u32 s66, s66, s69
	s_addc_u32 s67, s67, s68
	s_mov_b32 m0, s80
	s_waitcnt lgkmcnt(0)
	v_lshl_add_u64 v[134:135], s[66:67], 0, v[194:195]
	ds_read_b128 v[170:173], v241 offset:32768
	ds_read_b128 v[174:177], v241 offset:33792
	ds_read_b128 v[178:181], v241 offset:34816
	ds_read_b128 v[182:185], v241 offset:35840
	ds_read_b128 v[186:189], v241 offset:36864
	ds_read_b128 v[190:193], v241 offset:37888
	ds_read_b128 v[198:201], v241 offset:38912
	ds_read_b128 v[242:245], v241 offset:39936
	global_load_lds_dwordx4 v[134:135], off
	v_lshl_add_u64 v[134:135], s[66:67], 0, v[208:209]
	s_mov_b32 m0, s81
	s_nop 0
	global_load_lds_dwordx4 v[134:135], off
	s_waitcnt vmcnt(8)
	s_waitcnt lgkmcnt(0)
	s_barrier
	s_setprio 1
	s_waitcnt lgkmcnt(0)
	v_mfma_f32_16x16x32_bf16 v[114:117], v[154:157], v[170:173], v[114:117]
	v_mfma_f32_16x16x32_bf16 v[138:141], v[158:161], v[174:177], v[114:117]
	v_mfma_f32_16x16x32_bf16 v[114:117], v[162:165], v[170:173], v[126:129]
	v_mfma_f32_16x16x32_bf16 v[134:137], v[166:169], v[174:177], v[114:117]
	v_mfma_f32_16x16x32_bf16 v[114:117], v[154:157], v[178:181], v[122:125]
	v_mfma_f32_16x16x32_bf16 v[122:125], v[158:161], v[182:185], v[114:117]
	v_mfma_f32_16x16x32_bf16 v[114:117], v[162:165], v[178:181], v[118:121]
	v_mfma_f32_16x16x32_bf16 v[110:113], v[154:157], v[186:189], v[110:113]
	v_mfma_f32_16x16x32_bf16 v[106:109], v[162:165], v[186:189], v[106:109]
	v_mfma_f32_16x16x32_bf16 v[102:105], v[154:157], v[198:201], v[102:105]
	v_mfma_f32_16x16x32_bf16 v[98:101], v[162:165], v[198:201], v[98:101]
	v_mfma_f32_16x16x32_bf16 v[118:121], v[166:169], v[182:185], v[114:117]
	v_mfma_f32_16x16x32_bf16 v[110:113], v[158:161], v[190:193], v[110:113]
	v_mfma_f32_16x16x32_bf16 v[106:109], v[166:169], v[190:193], v[106:109]
	v_mfma_f32_16x16x32_bf16 v[102:105], v[158:161], v[242:245], v[102:105]
	v_mfma_f32_16x16x32_bf16 v[98:101], v[166:169], v[242:245], v[98:101]
	s_setprio 0
	s_setprio 1
	v_mfma_f32_16x16x32_bf16 v[86:89], v[130:133], v[170:173], v[86:89]
	v_mfma_f32_16x16x32_bf16 v[82:85], v[146:149], v[170:173], v[82:85]
	v_mfma_f32_16x16x32_bf16 v[68:71], v[130:133], v[178:181], v[68:71]
	v_mfma_f32_16x16x32_bf16 v[64:67], v[146:149], v[178:181], v[64:67]
	v_mfma_f32_16x16x32_bf16 v[52:55], v[130:133], v[186:189], v[52:55]
	v_mfma_f32_16x16x32_bf16 v[48:51], v[146:149], v[186:189], v[48:51]
	v_mfma_f32_16x16x32_bf16 v[36:39], v[130:133], v[198:201], v[36:39]
	v_mfma_f32_16x16x32_bf16 v[32:35], v[146:149], v[198:201], v[32:35]
	v_mfma_f32_16x16x32_bf16 v[86:89], v[142:145], v[174:177], v[86:89]
	v_mfma_f32_16x16x32_bf16 v[82:85], v[150:153], v[174:177], v[82:85]
	v_mfma_f32_16x16x32_bf16 v[68:71], v[142:145], v[182:185], v[68:71]
	v_mfma_f32_16x16x32_bf16 v[64:67], v[150:153], v[182:185], v[64:67]
	v_mfma_f32_16x16x32_bf16 v[52:55], v[142:145], v[190:193], v[52:55]
	v_mfma_f32_16x16x32_bf16 v[48:51], v[150:153], v[190:193], v[48:51]
	v_mfma_f32_16x16x32_bf16 v[36:39], v[142:145], v[242:245], v[36:39]
	v_mfma_f32_16x16x32_bf16 v[32:35], v[150:153], v[242:245], v[32:35]
	s_setprio 0
	s_barrier
	s_add_i32 s21, s21, s79
	v_lshl_add_u64 v[198:199], v[220:221], 0, s[18:19]
	s_mov_b32 m0, s21
	s_cmp_lg_u64 s[62:63], 0
	s_cbranch_scc0 .Lhm_go2
	ds_read_b128 v[186:189], v241 offset:49152
	ds_read_b128 v[190:193], v241 offset:50176
	ds_read_b128 v[178:181], v241 offset:51200
	ds_read_b128 v[182:185], v241 offset:52224
	ds_read_b128 v[170:173], v241 offset:53248
	ds_read_b128 v[174:177], v241 offset:54272
	ds_read_b128 v[114:117], v241 offset:55296
	ds_read_b128 v[126:129], v241 offset:56320
.Lhm_go2:
	global_load_lds_dwordx4 v[198:199], off
	s_add_i32 m0, s21, 0x2000
	s_add_u32 s64, s64, 0x40080
	v_lshl_add_u64 v[198:199], v[222:223], 0, s[18:19]
	s_addc_u32 s65, s65, 0
	s_add_i32 s21, s94, s79
	global_load_lds_dwordx4 v[198:199], off
	v_lshl_add_u64 v[198:199], s[64:65], 0, v[206:207]
	s_mov_b32 m0, s21
	s_and_b64 vcc, exec, s[36:37]
	global_load_lds_dwordx4 v[198:199], off
	v_lshl_add_u64 v[198:199], s[64:65], 0, v[210:211]
	s_add_i32 m0, s21, 0x2000
	s_nop 0
	global_load_lds_dwordx4 v[198:199], off
	v_lshl_add_u64 v[198:199], v[224:225], 0, s[18:19]
	s_mov_b32 m0, s84
	s_nop 0
	global_load_lds_dwordx4 v[198:199], off
	v_lshl_add_u64 v[198:199], v[226:227], 0, s[18:19]
	s_mov_b32 m0, s85
	s_nop 0
	global_load_lds_dwordx4 v[198:199], off
	s_waitcnt vmcnt(8)
	s_waitcnt lgkmcnt(0)
	s_barrier
	s_cbranch_vccnz .LBB0_67
	s_setprio 1
	s_waitcnt lgkmcnt(0)
	v_mfma_f32_16x16x32_bf16 v[94:97], v[154:157], v[186:189], v[94:97]
	v_mfma_f32_16x16x32_bf16 v[90:93], v[162:165], v[186:189], v[90:93]
	v_mfma_f32_16x16x32_bf16 v[76:79], v[154:157], v[178:181], v[76:79]
	v_mfma_f32_16x16x32_bf16 v[72:75], v[162:165], v[178:181], v[72:75]
	v_mfma_f32_16x16x32_bf16 v[60:63], v[154:157], v[170:173], v[60:63]
	v_mfma_f32_16x16x32_bf16 v[56:59], v[162:165], v[170:173], v[56:59]
	v_mfma_f32_16x16x32_bf16 v[44:47], v[154:157], v[114:117], v[44:47]
	v_mfma_f32_16x16x32_bf16 v[40:43], v[162:165], v[114:117], v[40:43]
	v_mfma_f32_16x16x32_bf16 v[94:97], v[158:161], v[190:193], v[94:97]
	v_mfma_f32_16x16x32_bf16 v[90:93], v[166:169], v[190:193], v[90:93]
	v_mfma_f32_16x16x32_bf16 v[76:79], v[158:161], v[182:185], v[76:79]
	v_mfma_f32_16x16x32_bf16 v[72:75], v[166:169], v[182:185], v[72:75]
	v_mfma_f32_16x16x32_bf16 v[60:63], v[158:161], v[174:177], v[60:63]
	v_mfma_f32_16x16x32_bf16 v[56:59], v[166:169], v[174:177], v[56:59]
	v_mfma_f32_16x16x32_bf16 v[44:47], v[158:161], v[126:129], v[44:47]
	v_mfma_f32_16x16x32_bf16 v[40:43], v[166:169], v[126:129], v[40:43]
	s_setprio 0
	s_setprio 1
	v_mfma_f32_16x16x32_bf16 v[28:31], v[130:133], v[186:189], v[28:31]
	v_mfma_f32_16x16x32_bf16 v[24:27], v[146:149], v[186:189], v[24:27]
	v_mfma_f32_16x16x32_bf16 v[20:23], v[130:133], v[178:181], v[20:23]
	v_mfma_f32_16x16x32_bf16 v[16:19], v[146:149], v[178:181], v[16:19]
	v_mfma_f32_16x16x32_bf16 v[12:15], v[130:133], v[170:173], v[12:15]
	v_mfma_f32_16x16x32_bf16 v[8:11], v[146:149], v[170:173], v[8:11]
	v_mfma_f32_16x16x32_bf16 v[4:7], v[130:133], v[114:117], v[4:7]
	v_mfma_f32_16x16x32_bf16 v[0:3], v[146:149], v[114:117], v[0:3]
	v_mfma_f32_16x16x32_bf16 v[28:31], v[142:145], v[190:193], v[28:31]
	v_mfma_f32_16x16x32_bf16 v[24:27], v[150:153], v[190:193], v[24:27]
	v_mfma_f32_16x16x32_bf16 v[20:23], v[142:145], v[182:185], v[20:23]
	v_mfma_f32_16x16x32_bf16 v[16:19], v[150:153], v[182:185], v[16:19]
	v_mfma_f32_16x16x32_bf16 v[12:15], v[142:145], v[174:177], v[12:15]
	v_mfma_f32_16x16x32_bf16 v[8:11], v[150:153], v[174:177], v[8:11]
	v_mfma_f32_16x16x32_bf16 v[4:7], v[142:145], v[126:129], v[4:7]
	v_mfma_f32_16x16x32_bf16 v[0:3], v[150:153], v[126:129], v[0:3]
	s_setprio 0
	s_branch .LBB0_67

.LBB0_607:
	s_add_u32 s36, s50, s52
	s_addc_u32 s37, s51, s53
	s_add_u32 s56, s36, 0x10000
	s_addc_u32 s57, s37, 0
	s_add_u32 s66, s91, s52
	s_addc_u32 s67, s96, s53
	s_add_i32 s94, 0, 0x10000
	s_cmp_eq_u32 s52, 0x1f0000
	s_cselect_b64 s[64:65], -1, 0
	s_and_b64 s[36:37], s[64:65], exec
	s_cselect_b32 s63, s39, s57
	s_cselect_b32 s62, s88, s56
	v_add_u32_e32 v80, s94, v220
	s_cselect_b32 s57, s25, s67
	s_cselect_b32 s56, s90, s66
	s_add_i32 s66, 0, 0x14000
	ds_read_b128 v[154:157], v80
	ds_read_b128 v[158:161], v80 offset:1024
	ds_read_b128 v[162:165], v80 offset:2048
	ds_read_b128 v[166:169], v80 offset:3072
	v_add_u32_e32 v80, s66, v220
	ds_read_b128 v[130:133], v80
	ds_read_b128 v[142:145], v80 offset:1024
	ds_read_b128 v[146:149], v80 offset:2048
	ds_read_b128 v[150:153], v80 offset:3072
	s_waitcnt lgkmcnt(0)
	v_lshl_add_u64 v[114:115], v[218:219], 0, s[52:53]
	s_add_i32 m0, s47, 0xc000
	ds_read_b128 v[170:173], v222
	ds_read_b128 v[174:177], v222 offset:1024
	ds_read_b128 v[178:181], v222 offset:2048
	ds_read_b128 v[182:185], v222 offset:3072
	ds_read_b128 v[186:189], v222 offset:4096
	ds_read_b128 v[190:193], v222 offset:5120
	ds_read_b128 v[224:227], v222 offset:6144
	ds_read_b128 v[240:243], v222 offset:7168
	global_load_lds_dwordx4 v[114:115], off
	v_lshl_add_u64 v[114:115], v[216:217], 0, s[52:53]
	s_add_i32 m0, s47, 0xe000
	s_nop 0
	global_load_lds_dwordx4 v[114:115], off
	s_waitcnt vmcnt(8)
	s_waitcnt lgkmcnt(0)
	s_barrier
	s_setprio 1
	s_waitcnt lgkmcnt(0)
	v_mfma_f32_16x16x32_bf16 v[114:117], v[154:157], v[170:173], v[138:141]
	v_mfma_f32_16x16x32_bf16 v[126:129], v[162:165], v[170:173], v[134:137]
	v_mfma_f32_16x16x32_bf16 v[122:125], v[154:157], v[178:181], v[122:125]
	v_mfma_f32_16x16x32_bf16 v[118:121], v[162:165], v[178:181], v[118:121]
	v_mfma_f32_16x16x32_bf16 v[110:113], v[154:157], v[186:189], v[110:113]
	v_mfma_f32_16x16x32_bf16 v[106:109], v[162:165], v[186:189], v[106:109]
	v_mfma_f32_16x16x32_bf16 v[102:105], v[154:157], v[224:227], v[102:105]
	v_mfma_f32_16x16x32_bf16 v[98:101], v[162:165], v[224:227], v[98:101]
	v_mfma_f32_16x16x32_bf16 v[114:117], v[158:161], v[174:177], v[114:117]
	v_mfma_f32_16x16x32_bf16 v[126:129], v[166:169], v[174:177], v[126:129]
	v_mfma_f32_16x16x32_bf16 v[122:125], v[158:161], v[182:185], v[122:125]
	v_mfma_f32_16x16x32_bf16 v[118:121], v[166:169], v[182:185], v[118:121]
	v_mfma_f32_16x16x32_bf16 v[110:113], v[158:161], v[190:193], v[110:113]
	v_mfma_f32_16x16x32_bf16 v[106:109], v[166:169], v[190:193], v[106:109]
	v_mfma_f32_16x16x32_bf16 v[102:105], v[158:161], v[240:243], v[102:105]
	v_mfma_f32_16x16x32_bf16 v[98:101], v[166:169], v[240:243], v[98:101]
	s_setprio 0
	s_setprio 1
	v_mfma_f32_16x16x32_bf16 v[86:89], v[130:133], v[170:173], v[86:89]
	v_mfma_f32_16x16x32_bf16 v[82:85], v[146:149], v[170:173], v[82:85]
	v_mfma_f32_16x16x32_bf16 v[68:71], v[130:133], v[178:181], v[68:71]
	v_mfma_f32_16x16x32_bf16 v[64:67], v[146:149], v[178:181], v[64:67]
	v_mfma_f32_16x16x32_bf16 v[52:55], v[130:133], v[186:189], v[52:55]
	v_mfma_f32_16x16x32_bf16 v[48:51], v[146:149], v[186:189], v[48:51]
	v_mfma_f32_16x16x32_bf16 v[36:39], v[130:133], v[224:227], v[36:39]
	v_mfma_f32_16x16x32_bf16 v[32:35], v[146:149], v[224:227], v[32:35]
	v_mfma_f32_16x16x32_bf16 v[86:89], v[142:145], v[174:177], v[86:89]
	v_mfma_f32_16x16x32_bf16 v[82:85], v[150:153], v[174:177], v[82:85]
	v_mfma_f32_16x16x32_bf16 v[68:71], v[142:145], v[182:185], v[68:71]
	v_mfma_f32_16x16x32_bf16 v[64:67], v[150:153], v[182:185], v[64:67]
	v_mfma_f32_16x16x32_bf16 v[52:55], v[142:145], v[190:193], v[52:55]
	v_mfma_f32_16x16x32_bf16 v[48:51], v[150:153], v[190:193], v[48:51]
	v_mfma_f32_16x16x32_bf16 v[36:39], v[142:145], v[240:243], v[36:39]
	v_mfma_f32_16x16x32_bf16 v[32:35], v[150:153], v[240:243], v[32:35]
	s_setprio 0
	s_barrier
	s_add_i32 s36, s94, s78
	v_lshl_add_u64 v[198:199], s[56:57], 0, v[206:207]
	s_mov_b32 m0, s36
	s_cmp_lg_u64 s[54:55], 0
	s_cbranch_scc0 .Lhm_ff21
	ds_read_b128 v[186:189], v222 offset:16384
	ds_read_b128 v[190:193], v222 offset:17408
	ds_read_b128 v[178:181], v222 offset:18432
	ds_read_b128 v[182:185], v222 offset:19456
	ds_read_b128 v[170:173], v222 offset:20480
	ds_read_b128 v[174:177], v222 offset:21504
	ds_read_b128 v[134:137], v222 offset:22528
	ds_read_b128 v[138:141], v222 offset:23552
.Lhm_ff21:
	global_load_lds_dwordx4 v[198:199], off
	s_add_i32 m0, s36, 0x2000
	s_add_u32 s36, s56, 0x4000
	v_lshl_add_u64 v[198:199], s[56:57], 0, v[210:211]
	s_addc_u32 s37, s57, 0
	s_add_i32 s66, s66, s78
	global_load_lds_dwordx4 v[198:199], off
	v_lshl_add_u64 v[198:199], s[36:37], 0, v[206:207]
	s_mov_b32 m0, s66
	v_cndmask_b32_e64 v80, 0, 1, s[54:55]
	global_load_lds_dwordx4 v[198:199], off
	v_lshl_add_u64 v[198:199], s[36:37], 0, v[210:211]
	s_add_i32 m0, s66, 0x2000
	v_cmp_ne_u32_e64 s[36:37], 1, v80
	global_load_lds_dwordx4 v[198:199], off
	v_lshl_add_u64 v[198:199], s[62:63], 0, v[194:195]
	s_mov_b32 m0, s47
	s_andn2_b64 vcc, exec, s[54:55]
	global_load_lds_dwordx4 v[198:199], off
	v_lshl_add_u64 v[198:199], s[62:63], 0, v[208:209]
	s_mov_b32 m0, s49
	s_nop 0
	global_load_lds_dwordx4 v[198:199], off
	s_waitcnt vmcnt(8)
	s_waitcnt lgkmcnt(0)
	s_barrier
	s_cbranch_vccnz .LBB0_609
	s_setprio 1
	s_waitcnt lgkmcnt(0)
	v_mfma_f32_16x16x32_bf16 v[94:97], v[154:157], v[186:189], v[94:97]
	v_mfma_f32_16x16x32_bf16 v[90:93], v[162:165], v[186:189], v[90:93]
	v_mfma_f32_16x16x32_bf16 v[76:79], v[154:157], v[178:181], v[76:79]
	v_mfma_f32_16x16x32_bf16 v[72:75], v[162:165], v[178:181], v[72:75]
	v_mfma_f32_16x16x32_bf16 v[60:63], v[154:157], v[170:173], v[60:63]
	v_mfma_f32_16x16x32_bf16 v[56:59], v[162:165], v[170:173], v[56:59]
	v_mfma_f32_16x16x32_bf16 v[44:47], v[154:157], v[134:137], v[44:47]
	v_mfma_f32_16x16x32_bf16 v[40:43], v[162:165], v[134:137], v[40:43]
	v_mfma_f32_16x16x32_bf16 v[94:97], v[158:161], v[190:193], v[94:97]
	v_mfma_f32_16x16x32_bf16 v[90:93], v[166:169], v[190:193], v[90:93]
	v_mfma_f32_16x16x32_bf16 v[76:79], v[158:161], v[182:185], v[76:79]
	v_mfma_f32_16x16x32_bf16 v[72:75], v[166:169], v[182:185], v[72:75]
	v_mfma_f32_16x16x32_bf16 v[60:63], v[158:161], v[174:177], v[60:63]
	v_mfma_f32_16x16x32_bf16 v[56:59], v[166:169], v[174:177], v[56:59]
	v_mfma_f32_16x16x32_bf16 v[44:47], v[158:161], v[138:141], v[44:47]
	v_mfma_f32_16x16x32_bf16 v[40:43], v[166:169], v[138:141], v[40:43]
	s_setprio 0
	s_setprio 1
	v_mfma_f32_16x16x32_bf16 v[28:31], v[130:133], v[186:189], v[28:31]
	v_mfma_f32_16x16x32_bf16 v[24:27], v[146:149], v[186:189], v[24:27]
	v_mfma_f32_16x16x32_bf16 v[20:23], v[130:133], v[178:181], v[20:23]
	v_mfma_f32_16x16x32_bf16 v[16:19], v[146:149], v[178:181], v[16:19]
	v_mfma_f32_16x16x32_bf16 v[12:15], v[130:133], v[170:173], v[12:15]
	v_mfma_f32_16x16x32_bf16 v[8:11], v[146:149], v[170:173], v[8:11]
	v_mfma_f32_16x16x32_bf16 v[4:7], v[130:133], v[134:137], v[4:7]
	v_mfma_f32_16x16x32_bf16 v[0:3], v[146:149], v[134:137], v[0:3]
	v_mfma_f32_16x16x32_bf16 v[28:31], v[142:145], v[190:193], v[28:31]
	v_mfma_f32_16x16x32_bf16 v[24:27], v[150:153], v[190:193], v[24:27]
	v_mfma_f32_16x16x32_bf16 v[20:23], v[142:145], v[182:185], v[20:23]
	v_mfma_f32_16x16x32_bf16 v[16:19], v[150:153], v[182:185], v[16:19]
	v_mfma_f32_16x16x32_bf16 v[12:15], v[142:145], v[174:177], v[12:15]
	v_mfma_f32_16x16x32_bf16 v[8:11], v[150:153], v[174:177], v[8:11]
	v_mfma_f32_16x16x32_bf16 v[4:7], v[142:145], v[138:141], v[4:7]
	v_mfma_f32_16x16x32_bf16 v[0:3], v[150:153], v[138:141], v[0:3]
	s_setprio 0
.LBB0_609:
	s_add_u32 s66, s62, 0x8000
	s_addc_u32 s67, s63, 0
	s_add_u32 s94, s56, 0x8000
	s_addc_u32 s95, s57, 0
	s_barrier
	s_add_i32 vcc_lo, 0, 0x18000
	v_add_u32_e32 v80, vcc_lo, v220
	s_add_i32 vcc_hi, 0, 0x1c000
	ds_read_b128 v[154:157], v80
	ds_read_b128 v[158:161], v80 offset:1024
	ds_read_b128 v[162:165], v80 offset:2048
	ds_read_b128 v[166:169], v80 offset:3072
	v_add_u32_e32 v80, vcc_hi, v220
	ds_read_b128 v[130:133], v80
	ds_read_b128 v[142:145], v80 offset:1024
	ds_read_b128 v[146:149], v80 offset:2048
	ds_read_b128 v[150:153], v80 offset:3072
	s_and_b64 s[64:65], s[42:43], s[64:65]
	s_and_b64 s[64:65], s[64:65], exec
	s_cselect_b32 s65, s89, s10
	s_cselect_b32 s64, 0, 0
	s_add_u32 s62, s62, s65
	s_addc_u32 s63, s63, s64
	s_mov_b32 m0, s79
	s_waitcnt lgkmcnt(0)
	v_lshl_add_u64 v[134:135], s[62:63], 0, v[194:195]
	ds_read_b128 v[170:173], v222 offset:32768
	ds_read_b128 v[174:177], v222 offset:33792
	ds_read_b128 v[178:181], v222 offset:34816
	ds_read_b128 v[182:185], v222 offset:35840
	ds_read_b128 v[186:189], v222 offset:36864
	ds_read_b128 v[190:193], v222 offset:37888
	ds_read_b128 v[224:227], v222 offset:38912
	ds_read_b128 v[240:243], v222 offset:39936
	global_load_lds_dwordx4 v[134:135], off
	v_lshl_add_u64 v[134:135], s[62:63], 0, v[208:209]
	s_mov_b32 m0, s80
	s_nop 0
	global_load_lds_dwordx4 v[134:135], off
	s_waitcnt vmcnt(8)
	s_waitcnt lgkmcnt(0)
	s_barrier
	s_setprio 1
	s_waitcnt lgkmcnt(0)
	v_mfma_f32_16x16x32_bf16 v[114:117], v[154:157], v[170:173], v[114:117]
	v_mfma_f32_16x16x32_bf16 v[138:141], v[158:161], v[174:177], v[114:117]
	v_mfma_f32_16x16x32_bf16 v[114:117], v[162:165], v[170:173], v[126:129]
	v_mfma_f32_16x16x32_bf16 v[134:137], v[166:169], v[174:177], v[114:117]
	v_mfma_f32_16x16x32_bf16 v[114:117], v[154:157], v[178:181], v[122:125]
	v_mfma_f32_16x16x32_bf16 v[122:125], v[158:161], v[182:185], v[114:117]
	v_mfma_f32_16x16x32_bf16 v[114:117], v[162:165], v[178:181], v[118:121]
	v_mfma_f32_16x16x32_bf16 v[110:113], v[154:157], v[186:189], v[110:113]
	v_mfma_f32_16x16x32_bf16 v[106:109], v[162:165], v[186:189], v[106:109]
	v_mfma_f32_16x16x32_bf16 v[102:105], v[154:157], v[224:227], v[102:105]
	v_mfma_f32_16x16x32_bf16 v[98:101], v[162:165], v[224:227], v[98:101]
	v_mfma_f32_16x16x32_bf16 v[118:121], v[166:169], v[182:185], v[114:117]
	v_mfma_f32_16x16x32_bf16 v[110:113], v[158:161], v[190:193], v[110:113]
	v_mfma_f32_16x16x32_bf16 v[106:109], v[166:169], v[190:193], v[106:109]
	v_mfma_f32_16x16x32_bf16 v[102:105], v[158:161], v[240:243], v[102:105]
	v_mfma_f32_16x16x32_bf16 v[98:101], v[166:169], v[240:243], v[98:101]
	s_setprio 0
	s_setprio 1
	v_mfma_f32_16x16x32_bf16 v[86:89], v[130:133], v[170:173], v[86:89]
	v_mfma_f32_16x16x32_bf16 v[82:85], v[146:149], v[170:173], v[82:85]
	v_mfma_f32_16x16x32_bf16 v[68:71], v[130:133], v[178:181], v[68:71]
	v_mfma_f32_16x16x32_bf16 v[64:67], v[146:149], v[178:181], v[64:67]
	v_mfma_f32_16x16x32_bf16 v[52:55], v[130:133], v[186:189], v[52:55]
	v_mfma_f32_16x16x32_bf16 v[48:51], v[146:149], v[186:189], v[48:51]
	v_mfma_f32_16x16x32_bf16 v[36:39], v[130:133], v[224:227], v[36:39]
	v_mfma_f32_16x16x32_bf16 v[32:35], v[146:149], v[224:227], v[32:35]
	v_mfma_f32_16x16x32_bf16 v[86:89], v[142:145], v[174:177], v[86:89]
	v_mfma_f32_16x16x32_bf16 v[82:85], v[150:153], v[174:177], v[82:85]
	v_mfma_f32_16x16x32_bf16 v[68:71], v[142:145], v[182:185], v[68:71]
	v_mfma_f32_16x16x32_bf16 v[64:67], v[150:153], v[182:185], v[64:67]
	v_mfma_f32_16x16x32_bf16 v[52:55], v[142:145], v[190:193], v[52:55]
	v_mfma_f32_16x16x32_bf16 v[48:51], v[150:153], v[190:193], v[48:51]
	v_mfma_f32_16x16x32_bf16 v[36:39], v[142:145], v[240:243], v[36:39]
	v_mfma_f32_16x16x32_bf16 v[32:35], v[150:153], v[240:243], v[32:35]
	s_setprio 0
	s_barrier
	s_add_i32 s62, vcc_lo, s78
	v_lshl_add_u64 v[198:199], s[94:95], 0, v[206:207]
	s_mov_b32 m0, s62
	s_cmp_lg_u64 s[54:55], 0
	s_cbranch_scc0 .Lhm_ff22
	ds_read_b128 v[186:189], v222 offset:49152
	ds_read_b128 v[190:193], v222 offset:50176
	ds_read_b128 v[178:181], v222 offset:51200
	ds_read_b128 v[182:185], v222 offset:52224
	ds_read_b128 v[170:173], v222 offset:53248
	ds_read_b128 v[174:177], v222 offset:54272
	ds_read_b128 v[114:117], v222 offset:55296
	ds_read_b128 v[126:129], v222 offset:56320
.Lhm_ff22:
	global_load_lds_dwordx4 v[198:199], off
	s_add_i32 m0, s62, 0x2000
	s_add_u32 s56, s56, 0xc000
	v_lshl_add_u64 v[198:199], s[94:95], 0, v[210:211]
	s_addc_u32 s57, s57, 0
	s_add_i32 s62, vcc_hi, s78
	global_load_lds_dwordx4 v[198:199], off
	v_lshl_add_u64 v[198:199], s[56:57], 0, v[206:207]
	s_mov_b32 m0, s62
	s_and_b64 vcc, exec, s[36:37]
	global_load_lds_dwordx4 v[198:199], off
	v_lshl_add_u64 v[198:199], s[56:57], 0, v[210:211]
	s_add_i32 m0, s62, 0x2000
	s_nop 0
	global_load_lds_dwordx4 v[198:199], off
	v_lshl_add_u64 v[198:199], s[66:67], 0, v[194:195]
	s_mov_b32 m0, s81
	s_nop 0
	global_load_lds_dwordx4 v[198:199], off
	v_lshl_add_u64 v[198:199], s[66:67], 0, v[208:209]
	s_mov_b32 m0, s82
	s_nop 0
	global_load_lds_dwordx4 v[198:199], off
	s_waitcnt vmcnt(8)
	s_waitcnt lgkmcnt(0)
	s_barrier
	s_cbranch_vccnz .LBB0_606
	s_setprio 1
	s_waitcnt lgkmcnt(0)
	v_mfma_f32_16x16x32_bf16 v[94:97], v[154:157], v[186:189], v[94:97]
	v_mfma_f32_16x16x32_bf16 v[90:93], v[162:165], v[186:189], v[90:93]
	v_mfma_f32_16x16x32_bf16 v[76:79], v[154:157], v[178:181], v[76:79]
	v_mfma_f32_16x16x32_bf16 v[72:75], v[162:165], v[178:181], v[72:75]
	v_mfma_f32_16x16x32_bf16 v[60:63], v[154:157], v[170:173], v[60:63]
	v_mfma_f32_16x16x32_bf16 v[56:59], v[162:165], v[170:173], v[56:59]
	v_mfma_f32_16x16x32_bf16 v[44:47], v[154:157], v[114:117], v[44:47]
	v_mfma_f32_16x16x32_bf16 v[40:43], v[162:165], v[114:117], v[40:43]
	v_mfma_f32_16x16x32_bf16 v[94:97], v[158:161], v[190:193], v[94:97]
	v_mfma_f32_16x16x32_bf16 v[90:93], v[166:169], v[190:193], v[90:93]
	v_mfma_f32_16x16x32_bf16 v[76:79], v[158:161], v[182:185], v[76:79]
	v_mfma_f32_16x16x32_bf16 v[72:75], v[166:169], v[182:185], v[72:75]
	v_mfma_f32_16x16x32_bf16 v[60:63], v[158:161], v[174:177], v[60:63]
	v_mfma_f32_16x16x32_bf16 v[56:59], v[166:169], v[174:177], v[56:59]
	v_mfma_f32_16x16x32_bf16 v[44:47], v[158:161], v[126:129], v[44:47]
	v_mfma_f32_16x16x32_bf16 v[40:43], v[166:169], v[126:129], v[40:43]
	s_setprio 0
	s_setprio 1
	v_mfma_f32_16x16x32_bf16 v[28:31], v[130:133], v[186:189], v[28:31]
	v_mfma_f32_16x16x32_bf16 v[24:27], v[146:149], v[186:189], v[24:27]
	v_mfma_f32_16x16x32_bf16 v[20:23], v[130:133], v[178:181], v[20:23]
	v_mfma_f32_16x16x32_bf16 v[16:19], v[146:149], v[178:181], v[16:19]
	v_mfma_f32_16x16x32_bf16 v[12:15], v[130:133], v[170:173], v[12:15]
	v_mfma_f32_16x16x32_bf16 v[8:11], v[146:149], v[170:173], v[8:11]
	v_mfma_f32_16x16x32_bf16 v[4:7], v[130:133], v[114:117], v[4:7]
	v_mfma_f32_16x16x32_bf16 v[0:3], v[146:149], v[114:117], v[0:3]
	v_mfma_f32_16x16x32_bf16 v[28:31], v[142:145], v[190:193], v[28:31]
	v_mfma_f32_16x16x32_bf16 v[24:27], v[150:153], v[190:193], v[24:27]
	v_mfma_f32_16x16x32_bf16 v[20:23], v[142:145], v[182:185], v[20:23]
	v_mfma_f32_16x16x32_bf16 v[16:19], v[150:153], v[182:185], v[16:19]
	v_mfma_f32_16x16x32_bf16 v[12:15], v[142:145], v[174:177], v[12:15]
	v_mfma_f32_16x16x32_bf16 v[8:11], v[150:153], v[174:177], v[8:11]
	v_mfma_f32_16x16x32_bf16 v[4:7], v[142:145], v[126:129], v[4:7]
	v_mfma_f32_16x16x32_bf16 v[0:3], v[150:153], v[126:129], v[0:3]
	s_setprio 0
	s_branch .LBB0_606
